# P0: weight transposes rewritten by hand: per-wave streaming, all loads up front, wave-private LDS transpose, 1KB-contiguous reads per block; loads issued before the misc section
# speedup vs baseline: 1.0374x; 1.0146x over previous
.LBB0_3:
	s_or_b64 exec, exec, s[4:5]
	s_ashr_i32 s3, s2, 31
	s_lshr_b32 s4, s3, 28
	s_add_i32 s4, s2, s4
	s_load_dwordx8 s[12:19], s[0:1], 0x0
	s_load_dwordx2 s[10:11], s[0:1], 0x20
	s_and_b32 s5, s4, 0x3fffff0
	s_sub_i32 s5, s2, s5
	s_lshl_b32 s8, s5, 6
	s_lshl_b32 s9, s4, 2
	s_andn2_b32 s9, s9, 63
	s_or_b32 s30, s8, 8
	s_or_b32 s27, s8, 16
	s_or_b32 s26, s8, 24
	s_or_b32 s25, s8, 32
	s_or_b32 s24, s8, 40
	s_or_b32 s23, s8, 48
	s_or_b32 s22, s8, 56
	s_cmpk_gt_i32 s2, 0x2ff
	v_mov_b32_e32 v3, v238
	s_branch .LBB0_52
	v_and_b32_e32 v1, 63, v3
	s_lshr_b32 s4, s9, 2
	v_or_b32_e32 v2, s9, v1
	s_and_b32 s4, s4, 32
	s_and_b32 s5, s9, 0xffffff00
	v_lshlrev_b32_e32 v2, 1, v2
	s_or_b32 s4, s4, s5
	v_and_b32_e32 v2, 0xc0, v2
	v_and_b32_e32 v6, 31, v3
	v_or3_b32 v2, s4, v2, v6
	s_movk_i32 s4, 0x4ff
	v_cmp_lt_i32_e32 vcc, s4, v2
	s_and_saveexec_b64 s[4:5], vcc
	s_cbranch_execz .LBB0_10
	s_cmpk_gt_u32 s9, 0xaff
	s_cbranch_scc0 .LBB0_7
	s_movk_i32 s6, 0xb18
	v_add_u32_e32 v4, 0xfffffa00, v2
	v_cmp_gt_u32_e32 vcc, s6, v2
	s_nop 1
	v_cndmask_b32_e32 v4, -1, v4, vcc
	s_cbranch_execz .LBB0_8
	s_branch .LBB0_9

.LBB0_52:
	s_load_dwordx8 s[44:51], s[0:1], 0x60
	s_waitcnt lgkmcnt(0)
	s_add_u32 s56, s52, 0x600000
	s_addc_u32 s57, s53, 0
	s_cmpk_gt_i32 s2, 0xff
	v_mov_b32_e32 v2, v238
	s_branch .LBB0_89
	v_and_b32_e32 v1, 63, v2
	v_ashrrev_i32_e32 v6, 6, v2
	v_or_b32_e32 v2, s9, v1
	s_movk_i32 s4, 0x400
	v_cmp_gt_i32_e32 vcc, s4, v2
	v_mov_b32_e32 v7, 0
	v_mov_b32_e32 v3, v7
	v_cndmask_b32_e32 v2, -1, v2, vcc
	v_cmp_lt_i32_e32 vcc, -1, v2
	s_waitcnt vmcnt(8)
	v_mov_b32_e32 v8, 0
	s_and_saveexec_b64 s[4:5], vcc
	s_cbranch_execz .LBB0_55
	v_add_u32_e32 v4, s8, v6
	v_ashrrev_i32_e32 v5, 31, v4
	v_lshlrev_b64 v[4:5], 12, v[4:5]
	v_lshl_add_u64 v[4:5], s[44:45], 0, v[4:5]
	v_lshl_add_u64 v[4:5], v[2:3], 2, v[4:5]
	global_load_dword v8, v[4:5], off

.LBB0_89:
	s_cmpk_lt_i32 s2, 0x400
	v_mov_b32_e32 v2, v238
	s_cselect_b64 s[30:31], -1, 0
	s_cmp_lg_u64 s[46:47], 0
	s_cselect_b64 s[16:17], -1, 0
	s_cmpk_gt_i32 s2, 0x3ff
	v_and_b32_e32 v1, 63, v2
	v_ashrrev_i32_e32 v2, 6, v2
	s_branch .LBB0_122
	v_or_b32_e32 v3, s9, v1
	s_movk_i32 s4, 0x1000
	v_cmp_gt_i32_e32 vcc, s4, v3
	v_mov_b32_e32 v5, 0
	v_add_u32_e32 v6, s8, v2
	v_cndmask_b32_e32 v4, -1, v3, vcc
	v_cmp_lt_i32_e64 s[4:5], -1, v4
	s_waitcnt vmcnt(8)
	v_ashrrev_i32_e32 v7, 31, v6
	v_mov_b32_e32 v8, v5
	s_and_saveexec_b64 s[6:7], s[4:5]
	s_cbranch_execz .LBB0_92
	v_lshlrev_b64 v[8:9], 14, v[6:7]
	v_lshl_add_u64 v[8:9], s[48:49], 0, v[8:9]
	v_lshl_add_u64 v[8:9], v[4:5], 2, v[8:9]
	global_load_dword v8, v[8:9], off

.LBB0_122:
	s_load_dwordx8 s[20:27], s[0:1], 0x38
	s_add_u32 s60, s52, 0x800000
	v_cndmask_b32_e64 v3, 0, 1, s[30:31]
	s_addc_u32 s61, s53, 0
	v_cmp_ne_u32_e64 s[54:55], 1, v3
	s_andn2_b64 vcc, exec, s[30:31]
	s_branch .LBB0_160
	v_lshlrev_b32_e32 v4, 1, v1
	v_mov_b32_e32 v5, 0
	s_waitcnt vmcnt(8)
	v_lshl_add_u32 v22, v1, 2, 0
	v_lshlrev_b32_e32 v3, 8, v1
	v_lshl_add_u64 v[6:7], s[60:61], 0, v[4:5]
	v_lshlrev_b32_e32 v4, 2, v2
	s_movk_i32 s4, 0x104
	v_add3_u32 v20, v22, v3, v4
	v_mul_lo_u32 v4, v2, s4
	s_lshl_b32 s34, s33, 6
	v_add_u32_e32 v22, v22, v4
	v_cndmask_b32_e64 v4, 0, 1, s[16:17]
	v_add_u32_e32 v13, 8, v2
	v_add_u32_e32 v14, 16, v2
	v_add_u32_e32 v15, 24, v2
	v_add_u32_e32 v16, 32, v2
	v_add_u32_e32 v17, 40, v2
	v_add_u32_e32 v18, 48, v2
	v_add_u32_e32 v19, 56, v2
	v_ashrrev_i32_e32 v3, 31, v2
	s_lshl_b32 s37, s2, 6
	v_add_u32_e32 v21, s34, v2
	s_movk_i32 s35, 0x1000
	v_cmp_ne_u32_e64 s[6:7], 1, v4
	s_mov_b32 s38, s2
	s_branch .LBB0_125

.LBB0_160:
	s_add_u32 s48, s52, 0x1000000
	s_addc_u32 s49, s53, 0
	v_mov_b32_e32 v4, v238
	s_and_b64 vcc, exec, s[54:55]
	s_branch .LBB0_197
	s_lshr_b32 s4, s3, 26
	s_add_i32 s4, s2, s4
	s_and_b32 s5, s4, 0xffffffc0
	v_bfi_b32 v2, 63, v4, s4
	s_movk_i32 s4, 0x400
	v_cmp_gt_i32_e32 vcc, s4, v2
	s_sub_i32 s5, s2, s5
	v_mov_b32_e32 v6, 0
	v_cndmask_b32_e32 v2, -1, v2, vcc
	v_ashrrev_i32_e32 v1, 6, v4
	s_lshl_b32 s6, s5, 6
	v_cmp_lt_i32_e32 vcc, -1, v2
	v_mov_b32_e32 v3, v6
	s_waitcnt vmcnt(8)
	v_mov_b32_e32 v7, 0
	s_and_saveexec_b64 s[4:5], vcc
	s_cbranch_execz .LBB0_163
	s_waitcnt vmcnt(0)
	v_add_u32_e32 v8, s6, v1
	v_ashrrev_i32_e32 v9, 31, v8
	v_lshlrev_b64 v[8:9], 12, v[8:9]
	v_lshl_add_u64 v[8:9], s[50:51], 0, v[8:9]
	v_lshl_add_u64 v[8:9], v[2:3], 2, v[8:9]
	global_load_dword v7, v[8:9], off

.LBB0_197:
	s_cmpk_lt_i32 s2, 0x80
	s_cselect_b64 s[8:9], -1, 0
	s_lshr_b32 s4, s3, 27
	s_add_i32 s4, s2, s4
	s_and_b32 s5, s4, 0x3ffffe0
	s_sub_i32 s5, s2, s5
	s_lshl_b32 s37, s5, 6
	s_lshl_b32 s38, s4, 1
	s_andn2_b32 s38, s38, 63
	s_or_b32 s36, s37, 8
	s_or_b32 s35, s37, 16
	s_or_b32 s34, s37, 24
	s_or_b32 s31, s37, 32
	s_or_b32 s30, s37, 40
	s_or_b32 s17, s37, 48
	s_or_b32 s16, s37, 56
	s_cmpk_gt_i32 s2, 0x7f
	v_mov_b32_e32 v2, v238
	s_branch .LBB0_234
	v_and_b32_e32 v1, 63, v2
	s_waitcnt vmcnt(8)
	v_ashrrev_i32_e32 v6, 6, v2
	v_or_b32_e32 v2, s38, v1
	s_movk_i32 s4, 0x100
	v_cmp_gt_i32_e32 vcc, s4, v2
	v_mov_b32_e32 v7, 0
	v_mov_b32_e32 v3, v7
	v_cndmask_b32_e32 v2, -1, v2, vcc
	v_cmp_lt_i32_e32 vcc, -1, v2
	s_waitcnt vmcnt(0)
	v_mov_b32_e32 v8, 0
	s_and_saveexec_b64 s[4:5], vcc
	s_cbranch_execz .LBB0_200
	v_add_u32_e32 v4, s37, v6
	v_ashrrev_i32_e32 v5, 31, v4
	v_lshlrev_b64 v[4:5], 10, v[4:5]
	s_waitcnt lgkmcnt(0)
	v_lshl_add_u64 v[4:5], s[20:21], 0, v[4:5]
	v_lshl_add_u64 v[4:5], v[2:3], 2, v[4:5]
	global_load_dword v8, v[4:5], off

.LBB0_234:
	v_cndmask_b32_e64 v1, 0, 1, s[8:9]
	v_mov_b32_e32 v2, v238
	v_cmp_ne_u32_e64 s[6:7], 1, v1
	s_andn2_b64 vcc, exec, s[8:9]
	s_branch .LBB0_271
	v_and_b32_e32 v1, 63, v2
	s_waitcnt vmcnt(8)
	v_ashrrev_i32_e32 v6, 6, v2
	v_or_b32_e32 v2, s38, v1
	s_movk_i32 s4, 0x100
	v_cmp_gt_i32_e32 vcc, s4, v2
	v_mov_b32_e32 v7, 0
	v_mov_b32_e32 v3, v7
	v_cndmask_b32_e32 v2, -1, v2, vcc
	v_cmp_lt_i32_e32 vcc, -1, v2
	s_waitcnt vmcnt(0)
	v_mov_b32_e32 v8, 0
	s_and_saveexec_b64 s[4:5], vcc
	s_cbranch_execz .LBB0_237
	v_add_u32_e32 v4, s37, v6
	v_ashrrev_i32_e32 v5, 31, v4
	v_lshlrev_b64 v[4:5], 10, v[4:5]
	s_waitcnt lgkmcnt(0)
	v_lshl_add_u64 v[4:5], s[24:25], 0, v[4:5]
	v_lshl_add_u64 v[4:5], v[2:3], 2, v[4:5]
	global_load_dword v8, v[4:5], off

.LBB0_271:
	s_cmp_lt_i32 s2, 8
	s_cselect_b64 s[8:9], -1, 0
	s_lshr_b32 s3, s3, 30
	s_add_i32 s3, s2, s3
	s_and_b32 s4, s3, 0x3fffffc
	s_sub_i32 s4, s2, s4
	s_lshl_b32 s34, s4, 6
	s_lshl_b32 s35, s3, 4
	s_andn2_b32 s35, s35, 63
	s_or_b32 s31, s34, 8
	s_or_b32 s30, s34, 16
	s_waitcnt lgkmcnt(0)
	s_or_b32 s25, s34, 24
	s_or_b32 s24, s34, 32
	s_or_b32 s21, s34, 40
	s_or_b32 s20, s34, 48
	s_or_b32 s3, s34, 56
	s_cmp_gt_i32 s2, 7
	v_mov_b32_e32 v2, v238
	s_branch .LBB0_308
	v_and_b32_e32 v1, 63, v2
	s_waitcnt vmcnt(8)
	v_ashrrev_i32_e32 v6, 6, v2
	v_or_b32_e32 v2, s35, v1
	v_cmp_gt_i32_e32 vcc, 64, v2
	v_mov_b32_e32 v7, 0
	v_mov_b32_e32 v3, v7
	v_cndmask_b32_e32 v2, -1, v2, vcc
	v_cmp_lt_i32_e32 vcc, -1, v2
	s_waitcnt vmcnt(0)
	v_mov_b32_e32 v8, 0
	s_and_saveexec_b64 s[4:5], vcc
	s_cbranch_execz .LBB0_274
	v_add_u32_e32 v4, s34, v6
	v_ashrrev_i32_e32 v5, 31, v4
	v_lshlrev_b64 v[4:5], 8, v[4:5]
	v_lshl_add_u64 v[4:5], s[22:23], 0, v[4:5]
	v_lshl_add_u64 v[4:5], v[2:3], 2, v[4:5]
	global_load_dword v8, v[4:5], off

.LBB0_308:
	v_mov_b32_e32 v2, v238
	s_andn2_b64 vcc, exec, s[8:9]
	s_branch .LBB0_345
	v_and_b32_e32 v1, 63, v2
	s_waitcnt vmcnt(8)
	v_ashrrev_i32_e32 v6, 6, v2
	v_or_b32_e32 v2, s35, v1
	v_cmp_gt_i32_e32 vcc, 64, v2
	v_mov_b32_e32 v7, 0
	v_mov_b32_e32 v3, v7
	v_cndmask_b32_e32 v2, -1, v2, vcc
	v_cmp_lt_i32_e32 vcc, -1, v2
	s_waitcnt vmcnt(0)
	v_mov_b32_e32 v8, 0
	s_and_saveexec_b64 s[4:5], vcc
	s_cbranch_execz .LBB0_311
	v_add_u32_e32 v4, s34, v6
	v_ashrrev_i32_e32 v5, 31, v4
	v_lshlrev_b64 v[4:5], 8, v[4:5]
	v_lshl_add_u64 v[4:5], s[26:27], 0, v[4:5]
	v_lshl_add_u64 v[4:5], v[2:3], 2, v[4:5]
	global_load_dword v8, v[4:5], off

.LBB0_345:
	s_load_dwordx8 s[68:75], s[0:1], 0x38
	s_load_dwordx8 s[92:99], s[0:1], 0x60
	s_load_dwordx2 s[20:21], s[0:1], 0x10
	v_readfirstlane_b32 s4, v238
	v_and_b32_e32 v1, 63, v238
	v_lshrrev_b32_e32 v2, 3, v1
	v_and_b32_e32 v3, 7, v1
	v_lshlrev_b32_e32 v58, 2, v3
	s_lshr_b32 s4, s4, 6
	s_lshl_b32 s41, s2, 3
	s_add_i32 s41, s41, s4
	s_mul_i32 s5, s4, 0x2100
	s_addk_i32 s5, 0x1000
	v_mul_u32_u24_e32 v56, 0x84, v2
	v_lshl_add_u32 v56, v3, 4, v56
	v_add_u32_e32 v56, s5, v56
	v_mul_u32_u24_e32 v57, 0x420, v3
	v_lshl_add_u32 v57, v2, 2, v57
	v_add_u32_e32 v57, s5, v57
	v_lshlrev_b32_e32 v13, 2, v2
	s_waitcnt lgkmcnt(0)
	s_cmpk_lt_u32 s41, 0x220
	s_cbranch_scc0 .Ltcx_no3a
	s_cmpk_lt_u32 s41, 0x100
	s_cbranch_scc0 .Ltcx_3n4
	s_mov_b64 s[62:63], s[68:69]
	s_mov_b32 s58, 0x1800000
	s_mov_b32 s59, s41
	s_branch .Ltcx_3sel
.Ltcx_3n4:
	s_cmpk_lt_u32 s41, 0x200
	s_cbranch_scc0 .Ltcx_3n5
	s_mov_b64 s[62:63], s[72:73]
	s_mov_b32 s58, 0x1900000
	s_sub_i32 s59, s41, 0x100
	s_branch .Ltcx_3sel
.Ltcx_3n5:
	s_cmpk_lt_u32 s41, 0x210
	s_cbranch_scc0 .Ltcx_3m7
	s_mov_b64 s[62:63], s[70:71]
	s_mov_b32 s58, 0x1a00000
	s_sub_i32 s59, s41, 0x200
	s_branch .Ltcx_3s67
.Ltcx_3m7:
	s_mov_b64 s[62:63], s[74:75]
	s_mov_b32 s58, 0x1a10000
	s_sub_i32 s59, s41, 0x210
.Ltcx_3s67:
	s_mov_b32 s65, 64
	s_movk_i32 s51, 0x100
	s_and_b32 s8, s59, 3
	s_lshr_b32 s9, s59, 2
	s_lshl_b32 s16, s9, 5
	s_cmp_lt_u32 s9, 2
	s_cselect_b32 s39, 32, 0
	s_cselect_b32 s16, s16, 0
	s_branch .Ltcx_3go
.Ltcx_3sel:
	s_movk_i32 s65, 0x100
	s_movk_i32 s51, 0x800
	s_lshr_b32 s8, s59, 3
	s_and_b32 s8, s8, 31
	s_lshr_b32 s9, s59, 8
	s_lshl_b32 s9, s9, 3
	s_and_b32 s17, s59, 7
	s_or_b32 s9, s9, s17
	s_mov_b32 s39, 32
	s_lshl_b32 s16, s9, 5
.Ltcx_3go:
	s_lshl_b32 s17, s8, 6
	s_lshl_b32 s76, s9, 5
	s_mul_i32 s77, s17, s65
	s_add_i32 s77, s77, s16
	s_lshl_b32 s77, s77, 2
	s_add_u32 s62, s62, s77
	s_addc_u32 s63, s63, 0
	s_lshl_b32 s64, s65, 5
	s_lshl_b32 s78, s65, 2
	s_mul_i32 s77, s76, s51
	s_add_i32 s77, s77, s17
	s_lshl_b32 s77, s77, 1
	s_add_u32 s34, s52, s58
	s_addc_u32 s35, s53, 0
	s_add_u32 s34, s34, s77
	s_addc_u32 s35, s35, 0
	s_lshl_b32 s36, s51, 4
	s_lshl_b32 s79, s51, 1
	v_mul_lo_u32 v8, v2, s78
	v_lshl_add_u32 v8, v3, 4, v8
	v_mul_lo_u32 v62, v2, s79
	v_lshl_add_u32 v62, v3, 4, v62
	global_load_dwordx4 v[196:199], v8, s[62:63]
	s_add_u32 s62, s62, s64
	s_addc_u32 s63, s63, 0
	global_load_dwordx4 v[200:203], v8, s[62:63]
	s_add_u32 s62, s62, s64
	s_addc_u32 s63, s63, 0
	global_load_dwordx4 v[204:207], v8, s[62:63]
	s_add_u32 s62, s62, s64
	s_addc_u32 s63, s63, 0
	global_load_dwordx4 v[208:211], v8, s[62:63]
	s_add_u32 s62, s62, s64
	s_addc_u32 s63, s63, 0
	global_load_dwordx4 v[212:215], v8, s[62:63]
	s_add_u32 s62, s62, s64
	s_addc_u32 s63, s63, 0
	global_load_dwordx4 v[216:219], v8, s[62:63]
	s_add_u32 s62, s62, s64
	s_addc_u32 s63, s63, 0
	global_load_dwordx4 v[220:223], v8, s[62:63]
	s_add_u32 s62, s62, s64
	s_addc_u32 s63, s63, 0
	global_load_dwordx4 v[224:227], v8, s[62:63]
.Ltcx_no3a:
	s_cmpk_lt_u32 s41, 0x600
	s_cbranch_scc0 .Ltcx_0m1
	s_mov_b64 s[62:63], s[20:21]
	s_mov_b32 s58, 0
	s_movk_i32 s65, 0xb18
	s_movk_i32 s51, 0x400
	s_lshr_b32 s8, s41, 3
	s_and_b32 s8, s8, 15
	s_lshr_b32 s9, s41, 7
	s_lshl_b32 s9, s9, 3
	s_and_b32 s17, s41, 7
	s_or_b32 s9, s9, s17
	s_and_b32 s16, s9, 7
	s_lshr_b32 s17, s9, 3
	s_lshl_b32 s17, s17, 8
	s_and_b32 s76, s16, 3
	s_lshl_b32 s76, s76, 6
	s_add_i32 s17, s17, s76
	s_lshr_b32 s76, s16, 2
	s_lshl_b32 s76, s76, 5
	s_add_i32 s17, s17, s76
	s_mov_b32 s37, 32
	s_mov_b32 s16, s17
	s_cmpk_lt_u32 s17, 0x500
	s_cbranch_scc1 .Ltcx_0go
	s_add_i32 s16, s17, 24
	s_cmpk_lt_u32 s17, 0xb00
	s_cbranch_scc1 .Ltcx_0go
	s_cmpk_eq_u32 s17, 0xb00
	s_cselect_b32 s16, 0x500, 0
	s_cselect_b32 s37, 24, 0
	s_branch .Ltcx_0go
.Ltcx_0m1:
	s_mov_b64 s[62:63], s[92:93]
	s_mov_b32 s58, 0x600000
	s_movk_i32 s65, 0x400
	s_movk_i32 s51, 0x400
	s_sub_i32 s59, s41, 0x600
	s_lshr_b32 s8, s59, 3
	s_and_b32 s8, s8, 15
	s_lshr_b32 s9, s59, 7
	s_lshl_b32 s9, s9, 3
	s_and_b32 s17, s59, 7
	s_or_b32 s9, s9, s17
	s_lshl_b32 s16, s9, 5
	s_mov_b32 s37, 32
.Ltcx_0go:
	s_lshl_b32 s17, s8, 6
	s_lshl_b32 s76, s9, 5
	s_mul_i32 s77, s17, s65
	s_add_i32 s77, s77, s16
	s_lshl_b32 s77, s77, 2
	s_add_u32 s62, s62, s77
	s_addc_u32 s63, s63, 0
	s_lshl_b32 s64, s65, 5
	s_lshl_b32 s78, s65, 2
	s_mul_i32 s77, s76, s51
	s_add_i32 s77, s77, s17
	s_lshl_b32 s77, s77, 1
	s_add_u32 s22, s52, s58
	s_addc_u32 s23, s53, 0
	s_add_u32 s22, s22, s77
	s_addc_u32 s23, s23, 0
	s_lshl_b32 s24, s51, 4
	s_lshl_b32 s79, s51, 1
	v_mul_lo_u32 v8, v2, s78
	v_lshl_add_u32 v8, v3, 4, v8
	v_mul_lo_u32 v59, v2, s79
	v_lshl_add_u32 v59, v3, 4, v59
	global_load_dwordx4 v[100:103], v8, s[62:63]
	s_add_u32 s62, s62, s64
	s_addc_u32 s63, s63, 0
	global_load_dwordx4 v[104:107], v8, s[62:63]
	s_add_u32 s62, s62, s64
	s_addc_u32 s63, s63, 0
	global_load_dwordx4 v[108:111], v8, s[62:63]
	s_add_u32 s62, s62, s64
	s_addc_u32 s63, s63, 0
	global_load_dwordx4 v[112:115], v8, s[62:63]
	s_add_u32 s62, s62, s64
	s_addc_u32 s63, s63, 0
	global_load_dwordx4 v[116:119], v8, s[62:63]
	s_add_u32 s62, s62, s64
	s_addc_u32 s63, s63, 0
	global_load_dwordx4 v[120:123], v8, s[62:63]
	s_add_u32 s62, s62, s64
	s_addc_u32 s63, s63, 0
	global_load_dwordx4 v[124:127], v8, s[62:63]
	s_add_u32 s62, s62, s64
	s_addc_u32 s63, s63, 0
	global_load_dwordx4 v[128:131], v8, s[62:63]
	s_lshr_b32 s8, s41, 3
	s_and_b32 s8, s8, 15
	s_lshr_b32 s9, s41, 7
	s_lshl_b32 s9, s9, 3
	s_and_b32 s17, s41, 7
	s_or_b32 s9, s9, s17
	s_lshl_b32 s17, s8, 8
	s_add_u32 s80, s94, s17
	s_addc_u32 s81, s95, 0
	global_load_dword v228, v13, s[80:81]
	global_load_dword v229, v13, s[80:81] offset:32
	global_load_dword v230, v13, s[80:81] offset:64
	global_load_dword v231, v13, s[80:81] offset:96
	global_load_dword v232, v13, s[80:81] offset:128
	global_load_dword v233, v13, s[80:81] offset:160
	global_load_dword v234, v13, s[80:81] offset:192
	global_load_dword v235, v13, s[80:81] offset:224
	s_mov_b64 s[62:63], s[96:97]
	s_mov_b32 s58, 0x800000
	s_movk_i32 s65, 0x1000
	s_movk_i32 s51, 0x400
	s_lshl_b32 s16, s9, 5
	s_lshl_b32 s17, s8, 6
	s_lshl_b32 s76, s9, 5
	s_mul_i32 s77, s17, s65
	s_add_i32 s77, s77, s16
	s_lshl_b32 s77, s77, 2
	s_add_u32 s62, s62, s77
	s_addc_u32 s63, s63, 0
	s_lshl_b32 s64, s65, 5
	s_lshl_b32 s78, s65, 2
	s_mul_i32 s77, s76, s51
	s_add_i32 s77, s77, s17
	s_lshl_b32 s77, s77, 1
	s_add_u32 s26, s52, s58
	s_addc_u32 s27, s53, 0
	s_add_u32 s26, s26, s77
	s_addc_u32 s27, s27, 0
	s_lshl_b32 s25, s51, 4
	s_lshl_b32 s79, s51, 1
	v_mul_lo_u32 v8, v2, s78
	v_lshl_add_u32 v8, v3, 4, v8
	v_mul_lo_u32 v60, v2, s79
	v_lshl_add_u32 v60, v3, 4, v60
	global_load_dwordx4 v[132:135], v8, s[62:63]
	s_add_u32 s62, s62, s64
	s_addc_u32 s63, s63, 0
	global_load_dwordx4 v[136:139], v8, s[62:63]
	s_add_u32 s62, s62, s64
	s_addc_u32 s63, s63, 0
	global_load_dwordx4 v[140:143], v8, s[62:63]
	s_add_u32 s62, s62, s64
	s_addc_u32 s63, s63, 0
	global_load_dwordx4 v[144:147], v8, s[62:63]
	s_add_u32 s62, s62, s64
	s_addc_u32 s63, s63, 0
	global_load_dwordx4 v[148:151], v8, s[62:63]
	s_add_u32 s62, s62, s64
	s_addc_u32 s63, s63, 0
	global_load_dwordx4 v[152:155], v8, s[62:63]
	s_add_u32 s62, s62, s64
	s_addc_u32 s63, s63, 0
	global_load_dwordx4 v[156:159], v8, s[62:63]
	s_add_u32 s62, s62, s64
	s_addc_u32 s63, s63, 0
	global_load_dwordx4 v[160:163], v8, s[62:63]
	s_mov_b64 s[62:63], s[98:99]
	s_mov_b32 s58, 0x1000000
	s_movk_i32 s65, 0x400
	s_movk_i32 s51, 0x1000
	s_lshr_b32 s8, s41, 3
	s_and_b32 s8, s8, 63
	s_lshr_b32 s9, s41, 9
	s_lshl_b32 s9, s9, 3
	s_and_b32 s17, s41, 7
	s_or_b32 s9, s9, s17
	s_lshl_b32 s16, s9, 5
	s_lshl_b32 s17, s8, 6
	s_lshl_b32 s76, s9, 5
	s_mul_i32 s77, s17, s65
	s_add_i32 s77, s77, s16
	s_lshl_b32 s77, s77, 2
	s_add_u32 s62, s62, s77
	s_addc_u32 s63, s63, 0
	s_lshl_b32 s64, s65, 5
	s_lshl_b32 s78, s65, 2
	s_mul_i32 s77, s76, s51
	s_add_i32 s77, s77, s17
	s_lshl_b32 s77, s77, 1
	s_add_u32 s30, s52, s58
	s_addc_u32 s31, s53, 0
	s_add_u32 s30, s30, s77
	s_addc_u32 s31, s31, 0
	s_lshl_b32 s32, s51, 4
	s_lshl_b32 s79, s51, 1
	v_mul_lo_u32 v8, v2, s78
	v_lshl_add_u32 v8, v3, 4, v8
	v_mul_lo_u32 v61, v2, s79
	v_lshl_add_u32 v61, v3, 4, v61
	global_load_dwordx4 v[164:167], v8, s[62:63]
	s_add_u32 s62, s62, s64
	s_addc_u32 s63, s63, 0
	global_load_dwordx4 v[168:171], v8, s[62:63]
	s_add_u32 s62, s62, s64
	s_addc_u32 s63, s63, 0
	global_load_dwordx4 v[172:175], v8, s[62:63]
	s_add_u32 s62, s62, s64
	s_addc_u32 s63, s63, 0
	global_load_dwordx4 v[176:179], v8, s[62:63]
	s_add_u32 s62, s62, s64
	s_addc_u32 s63, s63, 0
	global_load_dwordx4 v[180:183], v8, s[62:63]
	s_add_u32 s62, s62, s64
	s_addc_u32 s63, s63, 0
	global_load_dwordx4 v[184:187], v8, s[62:63]
	s_add_u32 s62, s62, s64
	s_addc_u32 s63, s63, 0
	global_load_dwordx4 v[188:191], v8, s[62:63]
	s_add_u32 s62, s62, s64
	s_addc_u32 s63, s63, 0
	global_load_dwordx4 v[192:195], v8, s[62:63]
	s_add_u32 s58, s52, 0x1baa0800
	s_waitcnt vmcnt(8)
	v_lshl_add_u32 v6, s2, 9, v238
	s_movk_i32 s3, 0x2000
	v_writelane_b32 v254, s48, 3
	s_addc_u32 s59, s53, 0
	v_cmp_gt_i32_e32 vcc, s3, v6
	s_lshl_b32 s3, s33, 9
	v_writelane_b32 v254, s49, 4
	s_and_saveexec_b64 s[4:5], vcc
	s_cbranch_execz .LBB0_348
	v_mov_b32_e32 v2, 0
	s_mov_b64 s[8:9], 0
	v_mov_b32_e32 v3, v2
	v_mov_b32_e32 v4, v2
	v_mov_b32_e32 v5, v2
	s_movk_i32 s16, 0x1fff
	s_waitcnt vmcnt(0)
	v_mov_b32_e32 v8, v6

.LBB0_359:
	s_waitcnt vmcnt(0)
	s_cmp_eq_u32 s37, 32
	s_cbranch_scc1 .Ltcx_nz0
	v_cmp_gt_u32_e32 vcc, s37, v58
	s_nop 1
	v_cndmask_b32_e32 v100, 0, v100, vcc
	v_cndmask_b32_e32 v101, 0, v101, vcc
	v_cndmask_b32_e32 v102, 0, v102, vcc
	v_cndmask_b32_e32 v103, 0, v103, vcc
	v_cndmask_b32_e32 v104, 0, v104, vcc
	v_cndmask_b32_e32 v105, 0, v105, vcc
	v_cndmask_b32_e32 v106, 0, v106, vcc
	v_cndmask_b32_e32 v107, 0, v107, vcc
	v_cndmask_b32_e32 v108, 0, v108, vcc
	v_cndmask_b32_e32 v109, 0, v109, vcc
	v_cndmask_b32_e32 v110, 0, v110, vcc
	v_cndmask_b32_e32 v111, 0, v111, vcc
	v_cndmask_b32_e32 v112, 0, v112, vcc
	v_cndmask_b32_e32 v113, 0, v113, vcc
	v_cndmask_b32_e32 v114, 0, v114, vcc
	v_cndmask_b32_e32 v115, 0, v115, vcc
	v_cndmask_b32_e32 v116, 0, v116, vcc
	v_cndmask_b32_e32 v117, 0, v117, vcc
	v_cndmask_b32_e32 v118, 0, v118, vcc
	v_cndmask_b32_e32 v119, 0, v119, vcc
	v_cndmask_b32_e32 v120, 0, v120, vcc
	v_cndmask_b32_e32 v121, 0, v121, vcc
	v_cndmask_b32_e32 v122, 0, v122, vcc
	v_cndmask_b32_e32 v123, 0, v123, vcc
	v_cndmask_b32_e32 v124, 0, v124, vcc
	v_cndmask_b32_e32 v125, 0, v125, vcc
	v_cndmask_b32_e32 v126, 0, v126, vcc
	v_cndmask_b32_e32 v127, 0, v127, vcc
	v_cndmask_b32_e32 v128, 0, v128, vcc
	v_cndmask_b32_e32 v129, 0, v129, vcc
	v_cndmask_b32_e32 v130, 0, v130, vcc
	v_cndmask_b32_e32 v131, 0, v131, vcc
.Ltcx_nz0:
	ds_write_b32 v56, v100
	ds_write_b32 v56, v101 offset:4
	ds_write_b32 v56, v102 offset:8
	ds_write_b32 v56, v103 offset:12
	ds_write_b32 v56, v104 offset:1056
	ds_write_b32 v56, v105 offset:1060
	ds_write_b32 v56, v106 offset:1064
	ds_write_b32 v56, v107 offset:1068
	ds_write_b32 v56, v108 offset:2112
	ds_write_b32 v56, v109 offset:2116
	ds_write_b32 v56, v110 offset:2120
	ds_write_b32 v56, v111 offset:2124
	ds_write_b32 v56, v112 offset:3168
	ds_write_b32 v56, v113 offset:3172
	ds_write_b32 v56, v114 offset:3176
	ds_write_b32 v56, v115 offset:3180
	ds_write_b32 v56, v116 offset:4224
	ds_write_b32 v56, v117 offset:4228
	ds_write_b32 v56, v118 offset:4232
	ds_write_b32 v56, v119 offset:4236
	ds_write_b32 v56, v120 offset:5280
	ds_write_b32 v56, v121 offset:5284
	ds_write_b32 v56, v122 offset:5288
	ds_write_b32 v56, v123 offset:5292
	ds_write_b32 v56, v124 offset:6336
	ds_write_b32 v56, v125 offset:6340
	ds_write_b32 v56, v126 offset:6344
	ds_write_b32 v56, v127 offset:6348
	ds_write_b32 v56, v128 offset:7392
	ds_write_b32 v56, v129 offset:7396
	ds_write_b32 v56, v130 offset:7400
	ds_write_b32 v56, v131 offset:7404
	s_waitcnt lgkmcnt(0)
	ds_read2_b32 v[8:9], v57 offset0:0 offset1:33
	ds_read2_b32 v[10:11], v57 offset0:66 offset1:99
	ds_read2_b32 v[12:13], v57 offset0:132 offset1:165
	ds_read2_b32 v[14:15], v57 offset0:198 offset1:231
	ds_read2_b32 v[16:17], v57 offset0:8 offset1:41
	ds_read2_b32 v[18:19], v57 offset0:74 offset1:107
	ds_read2_b32 v[20:21], v57 offset0:140 offset1:173
	ds_read2_b32 v[22:23], v57 offset0:206 offset1:239
	ds_read2_b32 v[24:25], v57 offset0:16 offset1:49
	ds_read2_b32 v[26:27], v57 offset0:82 offset1:115
	ds_read2_b32 v[28:29], v57 offset0:148 offset1:181
	ds_read2_b32 v[30:31], v57 offset0:214 offset1:247
	ds_read2_b32 v[32:33], v57 offset0:24 offset1:57
	ds_read2_b32 v[34:35], v57 offset0:90 offset1:123
	ds_read2_b32 v[36:37], v57 offset0:156 offset1:189
	ds_read2_b32 v[38:39], v57 offset0:222 offset1:255
	s_waitcnt lgkmcnt(12)
	v_cvt_pk_bf16_f32 v40, v8, v9
	v_cvt_pk_bf16_f32 v41, v10, v11
	v_cvt_pk_bf16_f32 v42, v12, v13
	v_cvt_pk_bf16_f32 v43, v14, v15
	global_store_dwordx4 v59, v[40:43], s[22:23]
	s_add_u32 s22, s22, s24
	s_addc_u32 s23, s23, 0
	s_waitcnt lgkmcnt(8)
	v_cvt_pk_bf16_f32 v44, v16, v17
	v_cvt_pk_bf16_f32 v45, v18, v19
	v_cvt_pk_bf16_f32 v46, v20, v21
	v_cvt_pk_bf16_f32 v47, v22, v23
	global_store_dwordx4 v59, v[44:47], s[22:23]
	s_add_u32 s22, s22, s24
	s_addc_u32 s23, s23, 0
	s_waitcnt lgkmcnt(4)
	v_cvt_pk_bf16_f32 v48, v24, v25
	v_cvt_pk_bf16_f32 v49, v26, v27
	v_cvt_pk_bf16_f32 v50, v28, v29
	v_cvt_pk_bf16_f32 v51, v30, v31
	global_store_dwordx4 v59, v[48:51], s[22:23]
	s_add_u32 s22, s22, s24
	s_addc_u32 s23, s23, 0
	s_waitcnt lgkmcnt(0)
	v_cvt_pk_bf16_f32 v52, v32, v33
	v_cvt_pk_bf16_f32 v53, v34, v35
	v_cvt_pk_bf16_f32 v54, v36, v37
	v_cvt_pk_bf16_f32 v55, v38, v39
	global_store_dwordx4 v59, v[52:55], s[22:23]
	v_mul_f32_e32 v132, v132, v228
	v_mul_f32_e32 v133, v133, v228
	v_mul_f32_e32 v134, v134, v228
	v_mul_f32_e32 v135, v135, v228
	v_mul_f32_e32 v136, v136, v229
	v_mul_f32_e32 v137, v137, v229
	v_mul_f32_e32 v138, v138, v229
	v_mul_f32_e32 v139, v139, v229
	v_mul_f32_e32 v140, v140, v230
	v_mul_f32_e32 v141, v141, v230
	v_mul_f32_e32 v142, v142, v230
	v_mul_f32_e32 v143, v143, v230
	v_mul_f32_e32 v144, v144, v231
	v_mul_f32_e32 v145, v145, v231
	v_mul_f32_e32 v146, v146, v231
	v_mul_f32_e32 v147, v147, v231
	v_mul_f32_e32 v148, v148, v232
	v_mul_f32_e32 v149, v149, v232
	v_mul_f32_e32 v150, v150, v232
	v_mul_f32_e32 v151, v151, v232
	v_mul_f32_e32 v152, v152, v233
	v_mul_f32_e32 v153, v153, v233
	v_mul_f32_e32 v154, v154, v233
	v_mul_f32_e32 v155, v155, v233
	v_mul_f32_e32 v156, v156, v234
	v_mul_f32_e32 v157, v157, v234
	v_mul_f32_e32 v158, v158, v234
	v_mul_f32_e32 v159, v159, v234
	v_mul_f32_e32 v160, v160, v235
	v_mul_f32_e32 v161, v161, v235
	v_mul_f32_e32 v162, v162, v235
	v_mul_f32_e32 v163, v163, v235
	ds_write_b32 v56, v132
	ds_write_b32 v56, v133 offset:4
	ds_write_b32 v56, v134 offset:8
	ds_write_b32 v56, v135 offset:12
	ds_write_b32 v56, v136 offset:1056
	ds_write_b32 v56, v137 offset:1060
	ds_write_b32 v56, v138 offset:1064
	ds_write_b32 v56, v139 offset:1068
	ds_write_b32 v56, v140 offset:2112
	ds_write_b32 v56, v141 offset:2116
	ds_write_b32 v56, v142 offset:2120
	ds_write_b32 v56, v143 offset:2124
	ds_write_b32 v56, v144 offset:3168
	ds_write_b32 v56, v145 offset:3172
	ds_write_b32 v56, v146 offset:3176
	ds_write_b32 v56, v147 offset:3180
	ds_write_b32 v56, v148 offset:4224
	ds_write_b32 v56, v149 offset:4228
	ds_write_b32 v56, v150 offset:4232
	ds_write_b32 v56, v151 offset:4236
	ds_write_b32 v56, v152 offset:5280
	ds_write_b32 v56, v153 offset:5284
	ds_write_b32 v56, v154 offset:5288
	ds_write_b32 v56, v155 offset:5292
	ds_write_b32 v56, v156 offset:6336
	ds_write_b32 v56, v157 offset:6340
	ds_write_b32 v56, v158 offset:6344
	ds_write_b32 v56, v159 offset:6348
	ds_write_b32 v56, v160 offset:7392
	ds_write_b32 v56, v161 offset:7396
	ds_write_b32 v56, v162 offset:7400
	ds_write_b32 v56, v163 offset:7404
	s_waitcnt lgkmcnt(0)
	ds_read2_b32 v[8:9], v57 offset0:0 offset1:33
	ds_read2_b32 v[10:11], v57 offset0:66 offset1:99
	ds_read2_b32 v[12:13], v57 offset0:132 offset1:165
	ds_read2_b32 v[14:15], v57 offset0:198 offset1:231
	ds_read2_b32 v[16:17], v57 offset0:8 offset1:41
	ds_read2_b32 v[18:19], v57 offset0:74 offset1:107
	ds_read2_b32 v[20:21], v57 offset0:140 offset1:173
	ds_read2_b32 v[22:23], v57 offset0:206 offset1:239
	ds_read2_b32 v[24:25], v57 offset0:16 offset1:49
	ds_read2_b32 v[26:27], v57 offset0:82 offset1:115
	ds_read2_b32 v[28:29], v57 offset0:148 offset1:181
	ds_read2_b32 v[30:31], v57 offset0:214 offset1:247
	ds_read2_b32 v[32:33], v57 offset0:24 offset1:57
	ds_read2_b32 v[34:35], v57 offset0:90 offset1:123
	ds_read2_b32 v[36:37], v57 offset0:156 offset1:189
	ds_read2_b32 v[38:39], v57 offset0:222 offset1:255
	s_waitcnt lgkmcnt(12)
	v_cvt_pk_bf16_f32 v40, v8, v9
	v_cvt_pk_bf16_f32 v41, v10, v11
	v_cvt_pk_bf16_f32 v42, v12, v13
	v_cvt_pk_bf16_f32 v43, v14, v15
	global_store_dwordx4 v60, v[40:43], s[26:27]
	s_add_u32 s26, s26, s25
	s_addc_u32 s27, s27, 0
	s_waitcnt lgkmcnt(8)
	v_cvt_pk_bf16_f32 v44, v16, v17
	v_cvt_pk_bf16_f32 v45, v18, v19
	v_cvt_pk_bf16_f32 v46, v20, v21
	v_cvt_pk_bf16_f32 v47, v22, v23
	global_store_dwordx4 v60, v[44:47], s[26:27]
	s_add_u32 s26, s26, s25
	s_addc_u32 s27, s27, 0
	s_waitcnt lgkmcnt(4)
	v_cvt_pk_bf16_f32 v48, v24, v25
	v_cvt_pk_bf16_f32 v49, v26, v27
	v_cvt_pk_bf16_f32 v50, v28, v29
	v_cvt_pk_bf16_f32 v51, v30, v31
	global_store_dwordx4 v60, v[48:51], s[26:27]
	s_add_u32 s26, s26, s25
	s_addc_u32 s27, s27, 0
	s_waitcnt lgkmcnt(0)
	v_cvt_pk_bf16_f32 v52, v32, v33
	v_cvt_pk_bf16_f32 v53, v34, v35
	v_cvt_pk_bf16_f32 v54, v36, v37
	v_cvt_pk_bf16_f32 v55, v38, v39
	global_store_dwordx4 v60, v[52:55], s[26:27]
	ds_write_b32 v56, v164
	ds_write_b32 v56, v165 offset:4
	ds_write_b32 v56, v166 offset:8
	ds_write_b32 v56, v167 offset:12
	ds_write_b32 v56, v168 offset:1056
	ds_write_b32 v56, v169 offset:1060
	ds_write_b32 v56, v170 offset:1064
	ds_write_b32 v56, v171 offset:1068
	ds_write_b32 v56, v172 offset:2112
	ds_write_b32 v56, v173 offset:2116
	ds_write_b32 v56, v174 offset:2120
	ds_write_b32 v56, v175 offset:2124
	ds_write_b32 v56, v176 offset:3168
	ds_write_b32 v56, v177 offset:3172
	ds_write_b32 v56, v178 offset:3176
	ds_write_b32 v56, v179 offset:3180
	ds_write_b32 v56, v180 offset:4224
	ds_write_b32 v56, v181 offset:4228
	ds_write_b32 v56, v182 offset:4232
	ds_write_b32 v56, v183 offset:4236
	ds_write_b32 v56, v184 offset:5280
	ds_write_b32 v56, v185 offset:5284
	ds_write_b32 v56, v186 offset:5288
	ds_write_b32 v56, v187 offset:5292
	ds_write_b32 v56, v188 offset:6336
	ds_write_b32 v56, v189 offset:6340
	ds_write_b32 v56, v190 offset:6344
	ds_write_b32 v56, v191 offset:6348
	ds_write_b32 v56, v192 offset:7392
	ds_write_b32 v56, v193 offset:7396
	ds_write_b32 v56, v194 offset:7400
	ds_write_b32 v56, v195 offset:7404
	s_waitcnt lgkmcnt(0)
	ds_read2_b32 v[8:9], v57 offset0:0 offset1:33
	ds_read2_b32 v[10:11], v57 offset0:66 offset1:99
	ds_read2_b32 v[12:13], v57 offset0:132 offset1:165
	ds_read2_b32 v[14:15], v57 offset0:198 offset1:231
	ds_read2_b32 v[16:17], v57 offset0:8 offset1:41
	ds_read2_b32 v[18:19], v57 offset0:74 offset1:107
	ds_read2_b32 v[20:21], v57 offset0:140 offset1:173
	ds_read2_b32 v[22:23], v57 offset0:206 offset1:239
	ds_read2_b32 v[24:25], v57 offset0:16 offset1:49
	ds_read2_b32 v[26:27], v57 offset0:82 offset1:115
	ds_read2_b32 v[28:29], v57 offset0:148 offset1:181
	ds_read2_b32 v[30:31], v57 offset0:214 offset1:247
	ds_read2_b32 v[32:33], v57 offset0:24 offset1:57
	ds_read2_b32 v[34:35], v57 offset0:90 offset1:123
	ds_read2_b32 v[36:37], v57 offset0:156 offset1:189
	ds_read2_b32 v[38:39], v57 offset0:222 offset1:255
	s_waitcnt lgkmcnt(12)
	v_cvt_pk_bf16_f32 v40, v8, v9
	v_cvt_pk_bf16_f32 v41, v10, v11
	v_cvt_pk_bf16_f32 v42, v12, v13
	v_cvt_pk_bf16_f32 v43, v14, v15
	global_store_dwordx4 v61, v[40:43], s[30:31]
	s_add_u32 s30, s30, s32
	s_addc_u32 s31, s31, 0
	s_waitcnt lgkmcnt(8)
	v_cvt_pk_bf16_f32 v44, v16, v17
	v_cvt_pk_bf16_f32 v45, v18, v19
	v_cvt_pk_bf16_f32 v46, v20, v21
	v_cvt_pk_bf16_f32 v47, v22, v23
	global_store_dwordx4 v61, v[44:47], s[30:31]
	s_add_u32 s30, s30, s32
	s_addc_u32 s31, s31, 0
	s_waitcnt lgkmcnt(4)
	v_cvt_pk_bf16_f32 v48, v24, v25
	v_cvt_pk_bf16_f32 v49, v26, v27
	v_cvt_pk_bf16_f32 v50, v28, v29
	v_cvt_pk_bf16_f32 v51, v30, v31
	global_store_dwordx4 v61, v[48:51], s[30:31]
	s_add_u32 s30, s30, s32
	s_addc_u32 s31, s31, 0
	s_waitcnt lgkmcnt(0)
	v_cvt_pk_bf16_f32 v52, v32, v33
	v_cvt_pk_bf16_f32 v53, v34, v35
	v_cvt_pk_bf16_f32 v54, v36, v37
	v_cvt_pk_bf16_f32 v55, v38, v39
	global_store_dwordx4 v61, v[52:55], s[30:31]
	s_cmpk_lt_u32 s41, 0x220
	s_cbranch_scc0 .Ltcx_done
	s_cmp_eq_u32 s39, 32
	s_cbranch_scc1 .Ltcx_nz3
	v_cmp_gt_u32_e32 vcc, s39, v58
	s_nop 1
	v_cndmask_b32_e32 v196, 0, v196, vcc
	v_cndmask_b32_e32 v197, 0, v197, vcc
	v_cndmask_b32_e32 v198, 0, v198, vcc
	v_cndmask_b32_e32 v199, 0, v199, vcc
	v_cndmask_b32_e32 v200, 0, v200, vcc
	v_cndmask_b32_e32 v201, 0, v201, vcc
	v_cndmask_b32_e32 v202, 0, v202, vcc
	v_cndmask_b32_e32 v203, 0, v203, vcc
	v_cndmask_b32_e32 v204, 0, v204, vcc
	v_cndmask_b32_e32 v205, 0, v205, vcc
	v_cndmask_b32_e32 v206, 0, v206, vcc
	v_cndmask_b32_e32 v207, 0, v207, vcc
	v_cndmask_b32_e32 v208, 0, v208, vcc
	v_cndmask_b32_e32 v209, 0, v209, vcc
	v_cndmask_b32_e32 v210, 0, v210, vcc
	v_cndmask_b32_e32 v211, 0, v211, vcc
	v_cndmask_b32_e32 v212, 0, v212, vcc
	v_cndmask_b32_e32 v213, 0, v213, vcc
	v_cndmask_b32_e32 v214, 0, v214, vcc
	v_cndmask_b32_e32 v215, 0, v215, vcc
	v_cndmask_b32_e32 v216, 0, v216, vcc
	v_cndmask_b32_e32 v217, 0, v217, vcc
	v_cndmask_b32_e32 v218, 0, v218, vcc
	v_cndmask_b32_e32 v219, 0, v219, vcc
	v_cndmask_b32_e32 v220, 0, v220, vcc
	v_cndmask_b32_e32 v221, 0, v221, vcc
	v_cndmask_b32_e32 v222, 0, v222, vcc
	v_cndmask_b32_e32 v223, 0, v223, vcc
	v_cndmask_b32_e32 v224, 0, v224, vcc
	v_cndmask_b32_e32 v225, 0, v225, vcc
	v_cndmask_b32_e32 v226, 0, v226, vcc
	v_cndmask_b32_e32 v227, 0, v227, vcc
.Ltcx_nz3:
	ds_write_b32 v56, v196
	ds_write_b32 v56, v197 offset:4
	ds_write_b32 v56, v198 offset:8
	ds_write_b32 v56, v199 offset:12
	ds_write_b32 v56, v200 offset:1056
	ds_write_b32 v56, v201 offset:1060
	ds_write_b32 v56, v202 offset:1064
	ds_write_b32 v56, v203 offset:1068
	ds_write_b32 v56, v204 offset:2112
	ds_write_b32 v56, v205 offset:2116
	ds_write_b32 v56, v206 offset:2120
	ds_write_b32 v56, v207 offset:2124
	ds_write_b32 v56, v208 offset:3168
	ds_write_b32 v56, v209 offset:3172
	ds_write_b32 v56, v210 offset:3176
	ds_write_b32 v56, v211 offset:3180
	ds_write_b32 v56, v212 offset:4224
	ds_write_b32 v56, v213 offset:4228
	ds_write_b32 v56, v214 offset:4232
	ds_write_b32 v56, v215 offset:4236
	ds_write_b32 v56, v216 offset:5280
	ds_write_b32 v56, v217 offset:5284
	ds_write_b32 v56, v218 offset:5288
	ds_write_b32 v56, v219 offset:5292
	ds_write_b32 v56, v220 offset:6336
	ds_write_b32 v56, v221 offset:6340
	ds_write_b32 v56, v222 offset:6344
	ds_write_b32 v56, v223 offset:6348
	ds_write_b32 v56, v224 offset:7392
	ds_write_b32 v56, v225 offset:7396
	ds_write_b32 v56, v226 offset:7400
	ds_write_b32 v56, v227 offset:7404
	s_waitcnt lgkmcnt(0)
	ds_read2_b32 v[8:9], v57 offset0:0 offset1:33
	ds_read2_b32 v[10:11], v57 offset0:66 offset1:99
	ds_read2_b32 v[12:13], v57 offset0:132 offset1:165
	ds_read2_b32 v[14:15], v57 offset0:198 offset1:231
	ds_read2_b32 v[16:17], v57 offset0:8 offset1:41
	ds_read2_b32 v[18:19], v57 offset0:74 offset1:107
	ds_read2_b32 v[20:21], v57 offset0:140 offset1:173
	ds_read2_b32 v[22:23], v57 offset0:206 offset1:239
	ds_read2_b32 v[24:25], v57 offset0:16 offset1:49
	ds_read2_b32 v[26:27], v57 offset0:82 offset1:115
	ds_read2_b32 v[28:29], v57 offset0:148 offset1:181
	ds_read2_b32 v[30:31], v57 offset0:214 offset1:247
	ds_read2_b32 v[32:33], v57 offset0:24 offset1:57
	ds_read2_b32 v[34:35], v57 offset0:90 offset1:123
	ds_read2_b32 v[36:37], v57 offset0:156 offset1:189
	ds_read2_b32 v[38:39], v57 offset0:222 offset1:255
	s_waitcnt lgkmcnt(12)
	v_cvt_pk_bf16_f32 v40, v8, v9
	v_cvt_pk_bf16_f32 v41, v10, v11
	v_cvt_pk_bf16_f32 v42, v12, v13
	v_cvt_pk_bf16_f32 v43, v14, v15
	global_store_dwordx4 v62, v[40:43], s[34:35]
	s_add_u32 s34, s34, s36
	s_addc_u32 s35, s35, 0
	s_waitcnt lgkmcnt(8)
	v_cvt_pk_bf16_f32 v44, v16, v17
	v_cvt_pk_bf16_f32 v45, v18, v19
	v_cvt_pk_bf16_f32 v46, v20, v21
	v_cvt_pk_bf16_f32 v47, v22, v23
	global_store_dwordx4 v62, v[44:47], s[34:35]
	s_add_u32 s34, s34, s36
	s_addc_u32 s35, s35, 0
	s_waitcnt lgkmcnt(4)
	v_cvt_pk_bf16_f32 v48, v24, v25
	v_cvt_pk_bf16_f32 v49, v26, v27
	v_cvt_pk_bf16_f32 v50, v28, v29
	v_cvt_pk_bf16_f32 v51, v30, v31
	global_store_dwordx4 v62, v[48:51], s[34:35]
	s_add_u32 s34, s34, s36
	s_addc_u32 s35, s35, 0
	s_waitcnt lgkmcnt(0)
	v_cvt_pk_bf16_f32 v52, v32, v33
	v_cvt_pk_bf16_f32 v53, v34, v35
	v_cvt_pk_bf16_f32 v54, v36, v37
	v_cvt_pk_bf16_f32 v55, v38, v39
	global_store_dwordx4 v62, v[52:55], s[34:35]
